# MLA prompt loop unrolled 6x with parity-static LDS offsets (no per-tile address VALU), cross-half max deferred to rescale path
# speedup vs baseline: 1.0470x; 1.0091x over previous
.Lst_first:
	v_mov_b32_e32 v154, v153
	s_nop 1
	v_permlane32_swap_b32_e32 v153, v154
	v_max_f32_e32 v153, v153, v154
	v_sub_f32_e32 v236, 0, v153
	v_sub_f32_e32 v237, 0, v153
	v_sub_f32_e32 v238, 0, v153
	v_sub_f32_e32 v239, 0, v153
	v_sub_f32_e32 v240, 0, v153
	v_sub_f32_e32 v241, 0, v153
	v_sub_f32_e32 v242, 0, v153
	v_sub_f32_e32 v243, 0, v153
	v_sub_f32_e32 v244, 0, v153
	v_sub_f32_e32 v245, 0, v153
	v_sub_f32_e32 v246, 0, v153
	v_sub_f32_e32 v247, 0, v153
	v_sub_f32_e32 v248, 0, v153
	v_sub_f32_e32 v249, 0, v153
	v_sub_f32_e32 v250, 0, v153
	v_sub_f32_e32 v251, 0, v153
	v_mov_b32_e32 v154, v153
	s_branch .Lst_subs_0
.Lst_entry:
	v_add_u32_e32 v216, s68, v143
	v_add_u32_e32 v216, 0x100, v216
	v_ashrrev_i32_e32 v217, 31, v216
	v_lshlrev_b64 v[218:219], 12, v[216:217]
	v_lshlrev_b64 v[216:217], 6, v[216:217]
	v_lshl_add_u64 v[216:217], v[126:127], 0, v[216:217]
	v_lshl_add_u64 v[218:219], v[128:129], 0, v[218:219]
	v_lshl_add_u64 v[216:217], v[216:217], 0, s[64:65]
	v_cndmask_b32_e64 v216, v216, v218, s[14:15]
	v_subrev_u32_e32 v190, s30, v216
	v_mov_b32_e32 v216, 0x1000
	v_mov_b32_e32 v217, 0x40000
	v_cndmask_b32_e64 v197, v216, v217, s[14:15]
	v_add_u32_e32 v216, s68, v146
	v_add_u32_e32 v216, 0x100, v216
	v_ashrrev_i32_e32 v217, 31, v216
	v_lshlrev_b64 v[218:219], 12, v[216:217]
	v_lshlrev_b64 v[216:217], 6, v[216:217]
	v_lshl_add_u64 v[216:217], v[130:131], 0, v[216:217]
	v_lshl_add_u64 v[218:219], v[132:133], 0, v[218:219]
	v_lshl_add_u64 v[216:217], v[216:217], 0, s[64:65]
	v_cndmask_b32_e64 v216, v216, v218, s[16:17]
	v_subrev_u32_e32 v191, s30, v216
	v_mov_b32_e32 v216, 0x1000
	v_mov_b32_e32 v217, 0x40000
	v_cndmask_b32_e64 v208, v216, v217, s[16:17]
	v_add_u32_e32 v216, s68, v139
	v_add_u32_e32 v216, 0x100, v216
	v_ashrrev_i32_e32 v217, 31, v216
	v_lshlrev_b64 v[218:219], 12, v[216:217]
	v_lshlrev_b64 v[216:217], 6, v[216:217]
	v_lshl_add_u64 v[216:217], v[134:135], 0, v[216:217]
	v_lshl_add_u64 v[218:219], v[136:137], 0, v[218:219]
	v_lshl_add_u64 v[216:217], v[216:217], 0, s[64:65]
	v_cndmask_b32_e64 v216, v216, v218, s[18:19]
	v_subrev_u32_e32 v196, s30, v216
	v_mov_b32_e32 v216, 0x1000
	v_mov_b32_e32 v217, 0x40000
	v_cndmask_b32_e64 v209, v216, v217, s[18:19]
	v_mov_b32_e32 v236, 0
	v_mov_b32_e32 v237, 0
	v_mov_b32_e32 v238, 0
	v_mov_b32_e32 v239, 0
	v_mov_b32_e32 v240, 0
	v_mov_b32_e32 v241, 0
	v_mov_b32_e32 v242, 0
	v_mov_b32_e32 v243, 0
	v_mov_b32_e32 v244, 0
	v_mov_b32_e32 v245, 0
	v_mov_b32_e32 v246, 0
	v_mov_b32_e32 v247, 0
	v_mov_b32_e32 v248, 0
	v_mov_b32_e32 v249, 0
	v_mov_b32_e32 v250, 0
	v_mov_b32_e32 v251, 0
	v_add_u32_e32 v194, v192, v142
	v_add_u32_e32 v195, v140, v141
	v_add_u32_e32 v203, v144, v145
	v_add_u32_e32 v252, v147, v148
	v_add_u32_e32 v253, v149, v150
.Lst_top:
	s_add_i32 s93, s69, 0
	s_cmp_gt_i32 s93, s50
	s_cbranch_scc1 .Lst_noqk0
	ds_read_b128 v[220:223], v194
	ds_read_b128 v[224:227], v194 offset:32
	ds_read_b128 v[228:231], v194 offset:64
	ds_read_b128 v[232:235], v194 offset:96
	ds_read_b128 v[126:129], v194 offset:256
	ds_read_b128 v[130:133], v194 offset:288
	ds_read_b128 v[134:137], v194 offset:10752
	ds_read_b128 v[212:215], v194 offset:10784
	ds_read_b128 v[154:157], v194 offset:10816
	ds_read_b128 v[158:161], v194 offset:10848
	ds_read_b128 v[204:207], v194 offset:11008
	ds_read_b128 v[186:189], v194 offset:11040
	s_waitcnt lgkmcnt(11)
	v_mfma_f32_32x32x16_bf16 v[48:63], v[220:223], v[64:67], v[236:251]
	s_waitcnt lgkmcnt(10)
	v_mfma_f32_32x32x16_bf16 v[48:63], v[224:227], v[68:71], v[48:63]
	s_waitcnt lgkmcnt(9)
	v_mfma_f32_32x32x16_bf16 v[48:63], v[228:231], v[72:75], v[48:63]
	s_waitcnt lgkmcnt(8)
	v_mfma_f32_32x32x16_bf16 v[48:63], v[232:235], v[76:79], v[48:63]
	s_waitcnt lgkmcnt(7)
	v_mfma_f32_32x32x16_bf16 v[48:63], v[126:129], v[80:83], v[48:63]
	s_waitcnt lgkmcnt(6)
	v_mfma_f32_32x32x16_bf16 v[48:63], v[130:133], v[84:87], v[48:63]
	s_waitcnt lgkmcnt(5)
	v_mfma_f32_32x32x16_bf16 v[32:47], v[134:137], v[64:67], v[236:251]
	s_waitcnt lgkmcnt(4)
	v_mfma_f32_32x32x16_bf16 v[32:47], v[212:215], v[68:71], v[32:47]
	s_waitcnt lgkmcnt(3)
	v_mfma_f32_32x32x16_bf16 v[32:47], v[154:157], v[72:75], v[32:47]
	s_waitcnt lgkmcnt(2)
	v_mfma_f32_32x32x16_bf16 v[32:47], v[158:161], v[76:79], v[32:47]
	s_waitcnt lgkmcnt(1)
	v_mfma_f32_32x32x16_bf16 v[32:47], v[204:207], v[80:83], v[32:47]
	s_waitcnt lgkmcnt(0)
	v_mfma_f32_32x32x16_bf16 v[32:47], v[186:189], v[84:87], v[32:47]
	v_max_f32_e32 v162, v48, v48
	v_max_f32_e32 v153, v49, v49
	v_max_f32_e32 v153, v162, v153
	v_max3_f32 v153, v153, v50, v51
	v_max3_f32 v153, v153, v52, v53
	v_max3_f32 v153, v153, v54, v55
	v_max3_f32 v153, v153, v56, v57
	v_max3_f32 v153, v153, v58, v59
	v_max3_f32 v153, v153, v60, v61
	v_max3_f32 v153, v153, v62, v63
	s_nop 1
	v_max3_f32 v153, v153, v32, v33
	v_max3_f32 v153, v153, v34, v35
	v_max3_f32 v153, v153, v36, v37
	v_max3_f32 v153, v153, v38, v39
	v_max3_f32 v153, v153, v40, v41
	v_max3_f32 v153, v153, v42, v43
	v_max3_f32 v153, v153, v44, v45
	v_max3_f32 v153, v153, v46, v47
.Lst_noqk0:
	s_cmp_gt_i32 s93, s50
	s_cbranch_scc1 .Lst_nosm0
	s_cmp_eq_u32 s93, 0
	s_cbranch_scc1 .Lst_first
	v_cmp_lt_f32_e32 vcc, 0x41000000, v153
	s_cbranch_vccz .Lst_norescale_0
	v_mov_b32_e32 v154, v153
	s_nop 1
	v_permlane32_swap_b32_e32 v153, v154
	v_max_f32_e32 v153, v153, v154
	v_max_f32_e32 v154, 0, v153
	v_exp_f32_e64 v152, -v154
	v_sub_f32_e32 v236, v236, v154
	v_sub_f32_e32 v237, v237, v154
	v_sub_f32_e32 v238, v238, v154
	v_sub_f32_e32 v239, v239, v154
	v_sub_f32_e32 v240, v240, v154
	v_sub_f32_e32 v241, v241, v154
	v_sub_f32_e32 v242, v242, v154
	v_sub_f32_e32 v243, v243, v154
	v_sub_f32_e32 v244, v244, v154
	v_sub_f32_e32 v245, v245, v154
	v_sub_f32_e32 v246, v246, v154
	v_sub_f32_e32 v247, v247, v154
	v_sub_f32_e32 v248, v248, v154
	v_sub_f32_e32 v249, v249, v154
	v_sub_f32_e32 v250, v250, v154
	v_sub_f32_e32 v251, v251, v154
	v_pk_mul_f32 v[30:31], v[30:31], v[152:153] op_sel_hi:[1,0]
	v_pk_mul_f32 v[28:29], v[28:29], v[152:153] op_sel_hi:[1,0]
	v_pk_mul_f32 v[26:27], v[26:27], v[152:153] op_sel_hi:[1,0]
	v_pk_mul_f32 v[24:25], v[24:25], v[152:153] op_sel_hi:[1,0]
	v_pk_mul_f32 v[22:23], v[22:23], v[152:153] op_sel_hi:[1,0]
	v_pk_mul_f32 v[20:21], v[20:21], v[152:153] op_sel_hi:[1,0]
	v_pk_mul_f32 v[18:19], v[18:19], v[152:153] op_sel_hi:[1,0]
	v_pk_mul_f32 v[16:17], v[16:17], v[152:153] op_sel_hi:[1,0]
	v_pk_mul_f32 v[14:15], v[14:15], v[152:153] op_sel_hi:[1,0]
	v_pk_mul_f32 v[12:13], v[12:13], v[152:153] op_sel_hi:[1,0]
	v_pk_mul_f32 v[10:11], v[10:11], v[152:153] op_sel_hi:[1,0]
	v_pk_mul_f32 v[8:9], v[8:9], v[152:153] op_sel_hi:[1,0]
	v_pk_mul_f32 v[6:7], v[6:7], v[152:153] op_sel_hi:[1,0]
	v_pk_mul_f32 v[4:5], v[4:5], v[152:153] op_sel_hi:[1,0]
	v_pk_mul_f32 v[2:3], v[2:3], v[152:153] op_sel_hi:[1,0]
	v_pk_mul_f32 v[0:1], v[0:1], v[152:153] op_sel_hi:[1,0]
	v_mul_f32_e32 v151, v151, v152

.Lst_norescale_0:
	v_exp_f32_e32 v170, v32
	v_exp_f32_e32 v171, v33
	v_exp_f32_e32 v172, v34
	v_exp_f32_e32 v173, v35
	v_exp_f32_e32 v174, v36
	v_exp_f32_e32 v175, v37
	v_exp_f32_e32 v176, v38
	v_exp_f32_e32 v158, v52
	v_exp_f32_e32 v177, v39
	v_exp_f32_e32 v159, v53
	v_exp_f32_e32 v178, v40
	v_exp_f32_e32 v160, v54
	v_exp_f32_e32 v179, v41
	v_exp_f32_e32 v48, v48
	v_exp_f32_e32 v49, v49
	v_exp_f32_e32 v50, v50
	v_exp_f32_e32 v51, v51
	v_exp_f32_e32 v161, v55
	v_exp_f32_e32 v180, v42
	v_exp_f32_e32 v162, v56
	v_exp_f32_e32 v181, v43
	ds_read_b64_tr_b16 v[36:37], v195 offset:128
	ds_read_b64_tr_b16 v[38:39], v195 offset:2816
	v_exp_f32_e32 v163, v57
	v_exp_f32_e32 v182, v44
	v_exp_f32_e32 v164, v58
	v_exp_f32_e32 v183, v45
	v_exp_f32_e32 v165, v59
	v_exp_f32_e32 v184, v46
	v_exp_f32_e32 v166, v60
	v_cvt_pk_bf16_f32 v32, v48, v49
	v_cvt_pk_bf16_f32 v33, v50, v51
	v_cvt_pk_bf16_f32 v34, v158, v159
	v_cvt_pk_bf16_f32 v35, v160, v161
	v_exp_f32_e32 v167, v61
	s_waitcnt lgkmcnt(0)
	v_mfma_f32_32x32x16_bf16 v[16:31], v[36:39], v[32:35], v[16:31]
	v_exp_f32_e32 v168, v62
	v_exp_f32_e32 v169, v63
	v_add_f32_e32 v153, v49, v48
	v_add_f32_e32 v153, v50, v153
	v_add_f32_e32 v153, v51, v153
	v_exp_f32_e32 v185, v47
	ds_read_b64_tr_b16 v[44:45], v195 offset:5504
	ds_read_b64_tr_b16 v[46:47], v195 offset:8192
	ds_read_b64_tr_b16 v[50:51], v195 offset:2880
	ds_read_b64_tr_b16 v[48:49], v195 offset:192
	v_cvt_pk_bf16_f32 v40, v162, v163
	v_cvt_pk_bf16_f32 v41, v164, v165
	v_cvt_pk_bf16_f32 v42, v166, v167
	v_cvt_pk_bf16_f32 v43, v168, v169
	ds_read_b64_tr_b16 v[52:53], v195 offset:10880
	ds_read_b64_tr_b16 v[54:55], v195 offset:13568
	ds_read_b64_tr_b16 v[58:59], v195 offset:8256
	ds_read_b64_tr_b16 v[56:57], v195 offset:5568
	s_waitcnt lgkmcnt(6)
	v_mfma_f32_32x32x16_bf16 v[16:31], v[44:47], v[40:43], v[16:31]
	v_cvt_pk_bf16_f32 v36, v170, v171
	v_cvt_pk_bf16_f32 v37, v172, v173
	v_cvt_pk_bf16_f32 v38, v174, v175
	v_cvt_pk_bf16_f32 v39, v176, v177
	ds_read_b64_tr_b16 v[44:45], v195 offset:16256
	ds_read_b64_tr_b16 v[46:47], v195 offset:18944
	ds_read_b64_tr_b16 v[62:63], v195 offset:13632
	ds_read_b64_tr_b16 v[60:61], v195 offset:10944
	ds_read_b64_tr_b16 v[156:157], v195 offset:19008
	ds_read_b64_tr_b16 v[154:155], v195 offset:16320
	s_waitcnt lgkmcnt(8)
	v_mfma_f32_32x32x16_bf16 v[16:31], v[52:55], v[36:39], v[16:31]
	v_cvt_pk_bf16_f32 v52, v178, v179
	v_cvt_pk_bf16_f32 v53, v180, v181
	v_cvt_pk_bf16_f32 v54, v182, v183
	v_cvt_pk_bf16_f32 v55, v184, v185
	v_mfma_f32_32x32x16_bf16 v[0:15], v[48:51], v[32:35], v[0:15]
	s_waitcnt lgkmcnt(4)
	v_mfma_f32_32x32x16_bf16 v[16:31], v[44:47], v[52:55], v[16:31]
	v_add_f32_e32 v44, v158, v153
	v_add_f32_e32 v44, v159, v44
	v_add_f32_e32 v44, v160, v44
	v_add_f32_e32 v44, v161, v44
	v_add_f32_e32 v44, v162, v44
	v_add_f32_e32 v44, v163, v44
	v_add_f32_e32 v44, v164, v44
	v_mfma_f32_32x32x16_bf16 v[0:15], v[56:59], v[40:43], v[0:15]
	v_add_f32_e32 v32, v165, v44
	v_add_f32_e32 v32, v166, v32
	v_add_f32_e32 v32, v167, v32
	v_add_f32_e32 v32, v168, v32
	v_add_f32_e32 v32, v169, v32
	v_add_f32_e32 v32, v170, v32
	v_add_f32_e32 v32, v171, v32
	s_waitcnt lgkmcnt(2)
	v_mfma_f32_32x32x16_bf16 v[0:15], v[60:63], v[36:39], v[0:15]
	v_add_f32_e32 v32, v172, v32
	v_add_f32_e32 v32, v173, v32
	v_add_f32_e32 v32, v174, v32
	v_add_f32_e32 v32, v175, v32
	v_add_f32_e32 v32, v176, v32
	v_add_f32_e32 v32, v177, v32
	v_add_f32_e32 v32, v178, v32
	v_add_f32_e32 v32, v179, v32
	s_waitcnt lgkmcnt(0)
	v_mfma_f32_32x32x16_bf16 v[0:15], v[154:157], v[52:55], v[0:15]
	v_add_f32_e32 v32, v180, v32
	v_add_f32_e32 v32, v181, v32
	v_add_f32_e32 v32, v182, v32
	v_add_f32_e32 v32, v183, v32
	v_add_f32_e32 v32, v184, v32
	v_add_f32_e32 v32, v185, v32
	v_add_f32_e32 v151, v151, v32
.Lst_nosm0:
	s_cmp_ge_u32 s93, s51
	s_cbranch_scc1 .Lst_a0_nost
	s_waitcnt vmcnt(0)
	s_and_saveexec_b64 s[66:67], s[8:9]
	s_cbranch_execz .Lst_a0_s1
	ds_write_b128 v203, v[100:103] offset:21504
.Lst_a0_s1:
	s_or_b64 exec, exec, s[66:67]
	s_and_saveexec_b64 s[66:67], s[10:11]
	s_cbranch_execz .Lst_a0_s2
	ds_write_b128 v252, v[104:107] offset:21504
.Lst_a0_s2:
	s_or_b64 exec, exec, s[66:67]
	s_and_saveexec_b64 s[66:67], s[12:13]
	s_cbranch_execz .Lst_a0_s3
	ds_write_b128 v253, v[108:111] offset:21504

.Lst_a0_nold:
.Lst_bar2_0:
	s_waitcnt lgkmcnt(0)
	s_barrier
	s_add_i32 s93, s69, 1
	s_cmp_ge_u32 s93, s47
	s_cbranch_scc1 .Lst_exit
	s_cmp_gt_i32 s93, s50
	s_cbranch_scc1 .Lst_noqk1
	ds_read_b128 v[220:223], v194 offset:21504
	ds_read_b128 v[224:227], v194 offset:21536
	ds_read_b128 v[228:231], v194 offset:21568
	ds_read_b128 v[232:235], v194 offset:21600
	ds_read_b128 v[126:129], v194 offset:21760
	ds_read_b128 v[130:133], v194 offset:21792
	ds_read_b128 v[134:137], v194 offset:32256
	ds_read_b128 v[212:215], v194 offset:32288
	ds_read_b128 v[154:157], v194 offset:32320
	ds_read_b128 v[158:161], v194 offset:32352
	ds_read_b128 v[204:207], v194 offset:32512
	ds_read_b128 v[186:189], v194 offset:32544
	s_waitcnt lgkmcnt(11)
	v_mfma_f32_32x32x16_bf16 v[48:63], v[220:223], v[64:67], v[236:251]
	s_waitcnt lgkmcnt(10)
	v_mfma_f32_32x32x16_bf16 v[48:63], v[224:227], v[68:71], v[48:63]
	s_waitcnt lgkmcnt(9)
	v_mfma_f32_32x32x16_bf16 v[48:63], v[228:231], v[72:75], v[48:63]
	s_waitcnt lgkmcnt(8)
	v_mfma_f32_32x32x16_bf16 v[48:63], v[232:235], v[76:79], v[48:63]
	s_waitcnt lgkmcnt(7)
	v_mfma_f32_32x32x16_bf16 v[48:63], v[126:129], v[80:83], v[48:63]
	s_waitcnt lgkmcnt(6)
	v_mfma_f32_32x32x16_bf16 v[48:63], v[130:133], v[84:87], v[48:63]
	s_waitcnt lgkmcnt(5)
	v_mfma_f32_32x32x16_bf16 v[32:47], v[134:137], v[64:67], v[236:251]
	s_waitcnt lgkmcnt(4)
	v_mfma_f32_32x32x16_bf16 v[32:47], v[212:215], v[68:71], v[32:47]
	s_waitcnt lgkmcnt(3)
	v_mfma_f32_32x32x16_bf16 v[32:47], v[154:157], v[72:75], v[32:47]
	s_waitcnt lgkmcnt(2)
	v_mfma_f32_32x32x16_bf16 v[32:47], v[158:161], v[76:79], v[32:47]
	s_waitcnt lgkmcnt(1)
	v_mfma_f32_32x32x16_bf16 v[32:47], v[204:207], v[80:83], v[32:47]
	s_waitcnt lgkmcnt(0)
	v_mfma_f32_32x32x16_bf16 v[32:47], v[186:189], v[84:87], v[32:47]
	v_max_f32_e32 v162, v48, v48
	v_max_f32_e32 v153, v49, v49
	v_max_f32_e32 v153, v162, v153
	v_max3_f32 v153, v153, v50, v51
	v_max3_f32 v153, v153, v52, v53
	v_max3_f32 v153, v153, v54, v55
	v_max3_f32 v153, v153, v56, v57
	v_max3_f32 v153, v153, v58, v59
	v_max3_f32 v153, v153, v60, v61
	v_max3_f32 v153, v153, v62, v63
	s_nop 1
	v_max3_f32 v153, v153, v32, v33
	v_max3_f32 v153, v153, v34, v35
	v_max3_f32 v153, v153, v36, v37
	v_max3_f32 v153, v153, v38, v39
	v_max3_f32 v153, v153, v40, v41
	v_max3_f32 v153, v153, v42, v43
	v_max3_f32 v153, v153, v44, v45
	v_max3_f32 v153, v153, v46, v47
.Lst_noqk1:
	s_cmp_gt_i32 s93, s50
	s_cbranch_scc1 .Lst_nosm1
	v_cmp_lt_f32_e32 vcc, 0x41000000, v153
	s_cbranch_vccz .Lst_norescale_1
	v_mov_b32_e32 v154, v153
	s_nop 1
	v_permlane32_swap_b32_e32 v153, v154
	v_max_f32_e32 v153, v153, v154
	v_max_f32_e32 v154, 0, v153
	v_exp_f32_e64 v152, -v154
	v_sub_f32_e32 v236, v236, v154
	v_sub_f32_e32 v237, v237, v154
	v_sub_f32_e32 v238, v238, v154
	v_sub_f32_e32 v239, v239, v154
	v_sub_f32_e32 v240, v240, v154
	v_sub_f32_e32 v241, v241, v154
	v_sub_f32_e32 v242, v242, v154
	v_sub_f32_e32 v243, v243, v154
	v_sub_f32_e32 v244, v244, v154
	v_sub_f32_e32 v245, v245, v154
	v_sub_f32_e32 v246, v246, v154
	v_sub_f32_e32 v247, v247, v154
	v_sub_f32_e32 v248, v248, v154
	v_sub_f32_e32 v249, v249, v154
	v_sub_f32_e32 v250, v250, v154
	v_sub_f32_e32 v251, v251, v154
	v_pk_mul_f32 v[30:31], v[30:31], v[152:153] op_sel_hi:[1,0]
	v_pk_mul_f32 v[28:29], v[28:29], v[152:153] op_sel_hi:[1,0]
	v_pk_mul_f32 v[26:27], v[26:27], v[152:153] op_sel_hi:[1,0]
	v_pk_mul_f32 v[24:25], v[24:25], v[152:153] op_sel_hi:[1,0]
	v_pk_mul_f32 v[22:23], v[22:23], v[152:153] op_sel_hi:[1,0]
	v_pk_mul_f32 v[20:21], v[20:21], v[152:153] op_sel_hi:[1,0]
	v_pk_mul_f32 v[18:19], v[18:19], v[152:153] op_sel_hi:[1,0]
	v_pk_mul_f32 v[16:17], v[16:17], v[152:153] op_sel_hi:[1,0]
	v_pk_mul_f32 v[14:15], v[14:15], v[152:153] op_sel_hi:[1,0]
	v_pk_mul_f32 v[12:13], v[12:13], v[152:153] op_sel_hi:[1,0]
	v_pk_mul_f32 v[10:11], v[10:11], v[152:153] op_sel_hi:[1,0]
	v_pk_mul_f32 v[8:9], v[8:9], v[152:153] op_sel_hi:[1,0]
	v_pk_mul_f32 v[6:7], v[6:7], v[152:153] op_sel_hi:[1,0]
	v_pk_mul_f32 v[4:5], v[4:5], v[152:153] op_sel_hi:[1,0]
	v_pk_mul_f32 v[2:3], v[2:3], v[152:153] op_sel_hi:[1,0]
	v_pk_mul_f32 v[0:1], v[0:1], v[152:153] op_sel_hi:[1,0]
	v_mul_f32_e32 v151, v151, v152

.Lst_norescale_1:
	v_exp_f32_e32 v170, v32
	v_exp_f32_e32 v171, v33
	v_exp_f32_e32 v172, v34
	v_exp_f32_e32 v173, v35
	v_exp_f32_e32 v174, v36
	v_exp_f32_e32 v175, v37
	v_exp_f32_e32 v176, v38
	v_exp_f32_e32 v158, v52
	v_exp_f32_e32 v177, v39
	v_exp_f32_e32 v159, v53
	v_exp_f32_e32 v178, v40
	v_exp_f32_e32 v160, v54
	v_exp_f32_e32 v179, v41
	v_exp_f32_e32 v48, v48
	v_exp_f32_e32 v49, v49
	v_exp_f32_e32 v50, v50
	v_exp_f32_e32 v51, v51
	v_exp_f32_e32 v161, v55
	v_exp_f32_e32 v180, v42
	v_exp_f32_e32 v162, v56
	v_exp_f32_e32 v181, v43
	ds_read_b64_tr_b16 v[36:37], v195 offset:21632
	ds_read_b64_tr_b16 v[38:39], v195 offset:24320
	v_exp_f32_e32 v163, v57
	v_exp_f32_e32 v182, v44
	v_exp_f32_e32 v164, v58
	v_exp_f32_e32 v183, v45
	v_exp_f32_e32 v165, v59
	v_exp_f32_e32 v184, v46
	v_exp_f32_e32 v166, v60
	v_cvt_pk_bf16_f32 v32, v48, v49
	v_cvt_pk_bf16_f32 v33, v50, v51
	v_cvt_pk_bf16_f32 v34, v158, v159
	v_cvt_pk_bf16_f32 v35, v160, v161
	v_exp_f32_e32 v167, v61
	s_waitcnt lgkmcnt(0)
	v_mfma_f32_32x32x16_bf16 v[16:31], v[36:39], v[32:35], v[16:31]
	v_exp_f32_e32 v168, v62
	v_exp_f32_e32 v169, v63
	v_add_f32_e32 v153, v49, v48
	v_add_f32_e32 v153, v50, v153
	v_add_f32_e32 v153, v51, v153
	v_exp_f32_e32 v185, v47
	ds_read_b64_tr_b16 v[44:45], v195 offset:27008
	ds_read_b64_tr_b16 v[46:47], v195 offset:29696
	ds_read_b64_tr_b16 v[50:51], v195 offset:24384
	ds_read_b64_tr_b16 v[48:49], v195 offset:21696
	v_cvt_pk_bf16_f32 v40, v162, v163
	v_cvt_pk_bf16_f32 v41, v164, v165
	v_cvt_pk_bf16_f32 v42, v166, v167
	v_cvt_pk_bf16_f32 v43, v168, v169
	ds_read_b64_tr_b16 v[52:53], v195 offset:32384
	ds_read_b64_tr_b16 v[54:55], v195 offset:35072
	ds_read_b64_tr_b16 v[58:59], v195 offset:29760
	ds_read_b64_tr_b16 v[56:57], v195 offset:27072
	s_waitcnt lgkmcnt(6)
	v_mfma_f32_32x32x16_bf16 v[16:31], v[44:47], v[40:43], v[16:31]
	v_cvt_pk_bf16_f32 v36, v170, v171
	v_cvt_pk_bf16_f32 v37, v172, v173
	v_cvt_pk_bf16_f32 v38, v174, v175
	v_cvt_pk_bf16_f32 v39, v176, v177
	ds_read_b64_tr_b16 v[44:45], v195 offset:37760
	ds_read_b64_tr_b16 v[46:47], v195 offset:40448
	ds_read_b64_tr_b16 v[62:63], v195 offset:35136
	ds_read_b64_tr_b16 v[60:61], v195 offset:32448
	ds_read_b64_tr_b16 v[156:157], v195 offset:40512
	ds_read_b64_tr_b16 v[154:155], v195 offset:37824
	s_waitcnt lgkmcnt(8)
	v_mfma_f32_32x32x16_bf16 v[16:31], v[52:55], v[36:39], v[16:31]
	v_cvt_pk_bf16_f32 v52, v178, v179
	v_cvt_pk_bf16_f32 v53, v180, v181
	v_cvt_pk_bf16_f32 v54, v182, v183
	v_cvt_pk_bf16_f32 v55, v184, v185
	v_mfma_f32_32x32x16_bf16 v[0:15], v[48:51], v[32:35], v[0:15]
	s_waitcnt lgkmcnt(4)
	v_mfma_f32_32x32x16_bf16 v[16:31], v[44:47], v[52:55], v[16:31]
	v_add_f32_e32 v44, v158, v153
	v_add_f32_e32 v44, v159, v44
	v_add_f32_e32 v44, v160, v44
	v_add_f32_e32 v44, v161, v44
	v_add_f32_e32 v44, v162, v44
	v_add_f32_e32 v44, v163, v44
	v_add_f32_e32 v44, v164, v44
	v_mfma_f32_32x32x16_bf16 v[0:15], v[56:59], v[40:43], v[0:15]
	v_add_f32_e32 v32, v165, v44
	v_add_f32_e32 v32, v166, v32
	v_add_f32_e32 v32, v167, v32
	v_add_f32_e32 v32, v168, v32
	v_add_f32_e32 v32, v169, v32
	v_add_f32_e32 v32, v170, v32
	v_add_f32_e32 v32, v171, v32
	s_waitcnt lgkmcnt(2)
	v_mfma_f32_32x32x16_bf16 v[0:15], v[60:63], v[36:39], v[0:15]
	v_add_f32_e32 v32, v172, v32
	v_add_f32_e32 v32, v173, v32
	v_add_f32_e32 v32, v174, v32
	v_add_f32_e32 v32, v175, v32
	v_add_f32_e32 v32, v176, v32
	v_add_f32_e32 v32, v177, v32
	v_add_f32_e32 v32, v178, v32
	v_add_f32_e32 v32, v179, v32
	s_waitcnt lgkmcnt(0)
	v_mfma_f32_32x32x16_bf16 v[0:15], v[154:157], v[52:55], v[0:15]
	v_add_f32_e32 v32, v180, v32
	v_add_f32_e32 v32, v181, v32
	v_add_f32_e32 v32, v182, v32
	v_add_f32_e32 v32, v183, v32
	v_add_f32_e32 v32, v184, v32
	v_add_f32_e32 v32, v185, v32
	v_add_f32_e32 v151, v151, v32
.Lst_nosm1:
	s_cmp_ge_u32 s93, s51
	s_cbranch_scc1 .Lst_a1_nost
	s_waitcnt vmcnt(0)
	s_and_saveexec_b64 s[66:67], s[8:9]
	s_cbranch_execz .Lst_a1_s1
	ds_write_b128 v203, v[112:115]
.Lst_a1_s1:
	s_or_b64 exec, exec, s[66:67]
	s_and_saveexec_b64 s[66:67], s[10:11]
	s_cbranch_execz .Lst_a1_s2
	ds_write_b128 v252, v[116:119]
.Lst_a1_s2:
	s_or_b64 exec, exec, s[66:67]
	s_and_saveexec_b64 s[66:67], s[12:13]
	s_cbranch_execz .Lst_a1_s3
	ds_write_b128 v253, v[120:123]

.Lst_a1_nold:
.Lst_bar2_1:
	s_waitcnt lgkmcnt(0)
	s_barrier
	s_add_i32 s93, s69, 2
	s_cmp_ge_u32 s93, s47
	s_cbranch_scc1 .Lst_exit
	s_cmp_gt_i32 s93, s50
	s_cbranch_scc1 .Lst_noqk2
	ds_read_b128 v[220:223], v194
	ds_read_b128 v[224:227], v194 offset:32
	ds_read_b128 v[228:231], v194 offset:64
	ds_read_b128 v[232:235], v194 offset:96
	ds_read_b128 v[126:129], v194 offset:256
	ds_read_b128 v[130:133], v194 offset:288
	ds_read_b128 v[134:137], v194 offset:10752
	ds_read_b128 v[212:215], v194 offset:10784
	ds_read_b128 v[154:157], v194 offset:10816
	ds_read_b128 v[158:161], v194 offset:10848
	ds_read_b128 v[204:207], v194 offset:11008
	ds_read_b128 v[186:189], v194 offset:11040
	s_waitcnt lgkmcnt(11)
	v_mfma_f32_32x32x16_bf16 v[48:63], v[220:223], v[64:67], v[236:251]
	s_waitcnt lgkmcnt(10)
	v_mfma_f32_32x32x16_bf16 v[48:63], v[224:227], v[68:71], v[48:63]
	s_waitcnt lgkmcnt(9)
	v_mfma_f32_32x32x16_bf16 v[48:63], v[228:231], v[72:75], v[48:63]
	s_waitcnt lgkmcnt(8)
	v_mfma_f32_32x32x16_bf16 v[48:63], v[232:235], v[76:79], v[48:63]
	s_waitcnt lgkmcnt(7)
	v_mfma_f32_32x32x16_bf16 v[48:63], v[126:129], v[80:83], v[48:63]
	s_waitcnt lgkmcnt(6)
	v_mfma_f32_32x32x16_bf16 v[48:63], v[130:133], v[84:87], v[48:63]
	s_waitcnt lgkmcnt(5)
	v_mfma_f32_32x32x16_bf16 v[32:47], v[134:137], v[64:67], v[236:251]
	s_waitcnt lgkmcnt(4)
	v_mfma_f32_32x32x16_bf16 v[32:47], v[212:215], v[68:71], v[32:47]
	s_waitcnt lgkmcnt(3)
	v_mfma_f32_32x32x16_bf16 v[32:47], v[154:157], v[72:75], v[32:47]
	s_waitcnt lgkmcnt(2)
	v_mfma_f32_32x32x16_bf16 v[32:47], v[158:161], v[76:79], v[32:47]
	s_waitcnt lgkmcnt(1)
	v_mfma_f32_32x32x16_bf16 v[32:47], v[204:207], v[80:83], v[32:47]
	s_waitcnt lgkmcnt(0)
	v_mfma_f32_32x32x16_bf16 v[32:47], v[186:189], v[84:87], v[32:47]
	v_max_f32_e32 v162, v48, v48
	v_max_f32_e32 v153, v49, v49
	v_max_f32_e32 v153, v162, v153
	v_max3_f32 v153, v153, v50, v51
	v_max3_f32 v153, v153, v52, v53
	v_max3_f32 v153, v153, v54, v55
	v_max3_f32 v153, v153, v56, v57
	v_max3_f32 v153, v153, v58, v59
	v_max3_f32 v153, v153, v60, v61
	v_max3_f32 v153, v153, v62, v63
	s_nop 1
	v_max3_f32 v153, v153, v32, v33
	v_max3_f32 v153, v153, v34, v35
	v_max3_f32 v153, v153, v36, v37
	v_max3_f32 v153, v153, v38, v39
	v_max3_f32 v153, v153, v40, v41
	v_max3_f32 v153, v153, v42, v43
	v_max3_f32 v153, v153, v44, v45
	v_max3_f32 v153, v153, v46, v47

.Lst_nosm2:
	s_cmp_ge_u32 s93, s51
	s_cbranch_scc1 .Lst_a2_nost
	s_waitcnt vmcnt(0)
	s_and_saveexec_b64 s[66:67], s[8:9]
	s_cbranch_execz .Lst_a2_s1
	ds_write_b128 v203, v[88:91] offset:21504
.Lst_a2_s1:
	s_or_b64 exec, exec, s[66:67]
	s_and_saveexec_b64 s[66:67], s[10:11]
	s_cbranch_execz .Lst_a2_s2
	ds_write_b128 v252, v[92:95] offset:21504
.Lst_a2_s2:
	s_or_b64 exec, exec, s[66:67]
	s_and_saveexec_b64 s[66:67], s[12:13]
	s_cbranch_execz .Lst_a2_s3
	ds_write_b128 v253, v[96:99] offset:21504

.Lst_a2_nold:
.Lst_bar2_2:
	s_waitcnt lgkmcnt(0)
	s_barrier
	s_add_i32 s93, s69, 3
	s_cmp_ge_u32 s93, s47
	s_cbranch_scc1 .Lst_exit
	s_cmp_gt_i32 s93, s50
	s_cbranch_scc1 .Lst_noqk3
	ds_read_b128 v[220:223], v194 offset:21504
	ds_read_b128 v[224:227], v194 offset:21536
	ds_read_b128 v[228:231], v194 offset:21568
	ds_read_b128 v[232:235], v194 offset:21600
	ds_read_b128 v[126:129], v194 offset:21760
	ds_read_b128 v[130:133], v194 offset:21792
	ds_read_b128 v[134:137], v194 offset:32256
	ds_read_b128 v[212:215], v194 offset:32288
	ds_read_b128 v[154:157], v194 offset:32320
	ds_read_b128 v[158:161], v194 offset:32352
	ds_read_b128 v[204:207], v194 offset:32512
	ds_read_b128 v[186:189], v194 offset:32544
	s_waitcnt lgkmcnt(11)
	v_mfma_f32_32x32x16_bf16 v[48:63], v[220:223], v[64:67], v[236:251]
	s_waitcnt lgkmcnt(10)
	v_mfma_f32_32x32x16_bf16 v[48:63], v[224:227], v[68:71], v[48:63]
	s_waitcnt lgkmcnt(9)
	v_mfma_f32_32x32x16_bf16 v[48:63], v[228:231], v[72:75], v[48:63]
	s_waitcnt lgkmcnt(8)
	v_mfma_f32_32x32x16_bf16 v[48:63], v[232:235], v[76:79], v[48:63]
	s_waitcnt lgkmcnt(7)
	v_mfma_f32_32x32x16_bf16 v[48:63], v[126:129], v[80:83], v[48:63]
	s_waitcnt lgkmcnt(6)
	v_mfma_f32_32x32x16_bf16 v[48:63], v[130:133], v[84:87], v[48:63]
	s_waitcnt lgkmcnt(5)
	v_mfma_f32_32x32x16_bf16 v[32:47], v[134:137], v[64:67], v[236:251]
	s_waitcnt lgkmcnt(4)
	v_mfma_f32_32x32x16_bf16 v[32:47], v[212:215], v[68:71], v[32:47]
	s_waitcnt lgkmcnt(3)
	v_mfma_f32_32x32x16_bf16 v[32:47], v[154:157], v[72:75], v[32:47]
	s_waitcnt lgkmcnt(2)
	v_mfma_f32_32x32x16_bf16 v[32:47], v[158:161], v[76:79], v[32:47]
	s_waitcnt lgkmcnt(1)
	v_mfma_f32_32x32x16_bf16 v[32:47], v[204:207], v[80:83], v[32:47]
	s_waitcnt lgkmcnt(0)
	v_mfma_f32_32x32x16_bf16 v[32:47], v[186:189], v[84:87], v[32:47]
	v_max_f32_e32 v162, v48, v48
	v_max_f32_e32 v153, v49, v49
	v_max_f32_e32 v153, v162, v153
	v_max3_f32 v153, v153, v50, v51
	v_max3_f32 v153, v153, v52, v53
	v_max3_f32 v153, v153, v54, v55
	v_max3_f32 v153, v153, v56, v57
	v_max3_f32 v153, v153, v58, v59
	v_max3_f32 v153, v153, v60, v61
	v_max3_f32 v153, v153, v62, v63
	s_nop 1
	v_max3_f32 v153, v153, v32, v33
	v_max3_f32 v153, v153, v34, v35
	v_max3_f32 v153, v153, v36, v37
	v_max3_f32 v153, v153, v38, v39
	v_max3_f32 v153, v153, v40, v41
	v_max3_f32 v153, v153, v42, v43
	v_max3_f32 v153, v153, v44, v45
	v_max3_f32 v153, v153, v46, v47

.Lst_nosm3:
	s_cmp_ge_u32 s93, s51
	s_cbranch_scc1 .Lst_a3_nost
	s_waitcnt vmcnt(0)
	s_and_saveexec_b64 s[66:67], s[8:9]
	s_cbranch_execz .Lst_a3_s1
	ds_write_b128 v203, v[100:103]
.Lst_a3_s1:
	s_or_b64 exec, exec, s[66:67]
	s_and_saveexec_b64 s[66:67], s[10:11]
	s_cbranch_execz .Lst_a3_s2
	ds_write_b128 v252, v[104:107]
.Lst_a3_s2:
	s_or_b64 exec, exec, s[66:67]
	s_and_saveexec_b64 s[66:67], s[12:13]
	s_cbranch_execz .Lst_a3_s3
	ds_write_b128 v253, v[108:111]

.Lst_a3_nold:
.Lst_bar2_3:
	s_waitcnt lgkmcnt(0)
	s_barrier
	s_add_i32 s93, s69, 4
	s_cmp_ge_u32 s93, s47
	s_cbranch_scc1 .Lst_exit
	s_cmp_gt_i32 s93, s50
	s_cbranch_scc1 .Lst_noqk4
	ds_read_b128 v[220:223], v194
	ds_read_b128 v[224:227], v194 offset:32
	ds_read_b128 v[228:231], v194 offset:64
	ds_read_b128 v[232:235], v194 offset:96
	ds_read_b128 v[126:129], v194 offset:256
	ds_read_b128 v[130:133], v194 offset:288
	ds_read_b128 v[134:137], v194 offset:10752
	ds_read_b128 v[212:215], v194 offset:10784
	ds_read_b128 v[154:157], v194 offset:10816
	ds_read_b128 v[158:161], v194 offset:10848
	ds_read_b128 v[204:207], v194 offset:11008
	ds_read_b128 v[186:189], v194 offset:11040
	s_waitcnt lgkmcnt(11)
	v_mfma_f32_32x32x16_bf16 v[48:63], v[220:223], v[64:67], v[236:251]
	s_waitcnt lgkmcnt(10)
	v_mfma_f32_32x32x16_bf16 v[48:63], v[224:227], v[68:71], v[48:63]
	s_waitcnt lgkmcnt(9)
	v_mfma_f32_32x32x16_bf16 v[48:63], v[228:231], v[72:75], v[48:63]
	s_waitcnt lgkmcnt(8)
	v_mfma_f32_32x32x16_bf16 v[48:63], v[232:235], v[76:79], v[48:63]
	s_waitcnt lgkmcnt(7)
	v_mfma_f32_32x32x16_bf16 v[48:63], v[126:129], v[80:83], v[48:63]
	s_waitcnt lgkmcnt(6)
	v_mfma_f32_32x32x16_bf16 v[48:63], v[130:133], v[84:87], v[48:63]
	s_waitcnt lgkmcnt(5)
	v_mfma_f32_32x32x16_bf16 v[32:47], v[134:137], v[64:67], v[236:251]
	s_waitcnt lgkmcnt(4)
	v_mfma_f32_32x32x16_bf16 v[32:47], v[212:215], v[68:71], v[32:47]
	s_waitcnt lgkmcnt(3)
	v_mfma_f32_32x32x16_bf16 v[32:47], v[154:157], v[72:75], v[32:47]
	s_waitcnt lgkmcnt(2)
	v_mfma_f32_32x32x16_bf16 v[32:47], v[158:161], v[76:79], v[32:47]
	s_waitcnt lgkmcnt(1)
	v_mfma_f32_32x32x16_bf16 v[32:47], v[204:207], v[80:83], v[32:47]
	s_waitcnt lgkmcnt(0)
	v_mfma_f32_32x32x16_bf16 v[32:47], v[186:189], v[84:87], v[32:47]
	v_max_f32_e32 v162, v48, v48
	v_max_f32_e32 v153, v49, v49
	v_max_f32_e32 v153, v162, v153
	v_max3_f32 v153, v153, v50, v51
	v_max3_f32 v153, v153, v52, v53
	v_max3_f32 v153, v153, v54, v55
	v_max3_f32 v153, v153, v56, v57
	v_max3_f32 v153, v153, v58, v59
	v_max3_f32 v153, v153, v60, v61
	v_max3_f32 v153, v153, v62, v63
	s_nop 1
	v_max3_f32 v153, v153, v32, v33
	v_max3_f32 v153, v153, v34, v35
	v_max3_f32 v153, v153, v36, v37
	v_max3_f32 v153, v153, v38, v39
	v_max3_f32 v153, v153, v40, v41
	v_max3_f32 v153, v153, v42, v43
	v_max3_f32 v153, v153, v44, v45
	v_max3_f32 v153, v153, v46, v47

.Lst_nosm4:
	s_cmp_ge_u32 s93, s51
	s_cbranch_scc1 .Lst_a4_nost
	s_waitcnt vmcnt(0)
	s_and_saveexec_b64 s[66:67], s[8:9]
	s_cbranch_execz .Lst_a4_s1
	ds_write_b128 v203, v[112:115] offset:21504
.Lst_a4_s1:
	s_or_b64 exec, exec, s[66:67]
	s_and_saveexec_b64 s[66:67], s[10:11]
	s_cbranch_execz .Lst_a4_s2
	ds_write_b128 v252, v[116:119] offset:21504
.Lst_a4_s2:
	s_or_b64 exec, exec, s[66:67]
	s_and_saveexec_b64 s[66:67], s[12:13]
	s_cbranch_execz .Lst_a4_s3
	ds_write_b128 v253, v[120:123] offset:21504

.Lst_a4_nold:
.Lst_bar2_4:
	s_waitcnt lgkmcnt(0)
	s_barrier
	s_add_i32 s93, s69, 5
	s_cmp_ge_u32 s93, s47
	s_cbranch_scc1 .Lst_exit
	s_cmp_gt_i32 s93, s50
	s_cbranch_scc1 .Lst_noqk5
	ds_read_b128 v[220:223], v194 offset:21504
	ds_read_b128 v[224:227], v194 offset:21536
	ds_read_b128 v[228:231], v194 offset:21568
	ds_read_b128 v[232:235], v194 offset:21600
	ds_read_b128 v[126:129], v194 offset:21760
	ds_read_b128 v[130:133], v194 offset:21792
	ds_read_b128 v[134:137], v194 offset:32256
	ds_read_b128 v[212:215], v194 offset:32288
	ds_read_b128 v[154:157], v194 offset:32320
	ds_read_b128 v[158:161], v194 offset:32352
	ds_read_b128 v[204:207], v194 offset:32512
	ds_read_b128 v[186:189], v194 offset:32544
	s_waitcnt lgkmcnt(11)
	v_mfma_f32_32x32x16_bf16 v[48:63], v[220:223], v[64:67], v[236:251]
	s_waitcnt lgkmcnt(10)
	v_mfma_f32_32x32x16_bf16 v[48:63], v[224:227], v[68:71], v[48:63]
	s_waitcnt lgkmcnt(9)
	v_mfma_f32_32x32x16_bf16 v[48:63], v[228:231], v[72:75], v[48:63]
	s_waitcnt lgkmcnt(8)
	v_mfma_f32_32x32x16_bf16 v[48:63], v[232:235], v[76:79], v[48:63]
	s_waitcnt lgkmcnt(7)
	v_mfma_f32_32x32x16_bf16 v[48:63], v[126:129], v[80:83], v[48:63]
	s_waitcnt lgkmcnt(6)
	v_mfma_f32_32x32x16_bf16 v[48:63], v[130:133], v[84:87], v[48:63]
	s_waitcnt lgkmcnt(5)
	v_mfma_f32_32x32x16_bf16 v[32:47], v[134:137], v[64:67], v[236:251]
	s_waitcnt lgkmcnt(4)
	v_mfma_f32_32x32x16_bf16 v[32:47], v[212:215], v[68:71], v[32:47]
	s_waitcnt lgkmcnt(3)
	v_mfma_f32_32x32x16_bf16 v[32:47], v[154:157], v[72:75], v[32:47]
	s_waitcnt lgkmcnt(2)
	v_mfma_f32_32x32x16_bf16 v[32:47], v[158:161], v[76:79], v[32:47]
	s_waitcnt lgkmcnt(1)
	v_mfma_f32_32x32x16_bf16 v[32:47], v[204:207], v[80:83], v[32:47]
	s_waitcnt lgkmcnt(0)
	v_mfma_f32_32x32x16_bf16 v[32:47], v[186:189], v[84:87], v[32:47]
	v_max_f32_e32 v162, v48, v48
	v_max_f32_e32 v153, v49, v49
	v_max_f32_e32 v153, v162, v153
	v_max3_f32 v153, v153, v50, v51
	v_max3_f32 v153, v153, v52, v53
	v_max3_f32 v153, v153, v54, v55
	v_max3_f32 v153, v153, v56, v57
	v_max3_f32 v153, v153, v58, v59
	v_max3_f32 v153, v153, v60, v61
	v_max3_f32 v153, v153, v62, v63
	s_nop 1
	v_max3_f32 v153, v153, v32, v33
	v_max3_f32 v153, v153, v34, v35
	v_max3_f32 v153, v153, v36, v37
	v_max3_f32 v153, v153, v38, v39
	v_max3_f32 v153, v153, v40, v41
	v_max3_f32 v153, v153, v42, v43
	v_max3_f32 v153, v153, v44, v45
	v_max3_f32 v153, v153, v46, v47

.Lst_nosm5:
	s_cmp_ge_u32 s93, s51
	s_cbranch_scc1 .Lst_a5_nost
	s_waitcnt vmcnt(0)
	s_and_saveexec_b64 s[66:67], s[8:9]
	s_cbranch_execz .Lst_a5_s1
	ds_write_b128 v203, v[88:91]
.Lst_a5_s1:
	s_or_b64 exec, exec, s[66:67]
	s_and_saveexec_b64 s[66:67], s[10:11]
	s_cbranch_execz .Lst_a5_s2
	ds_write_b128 v252, v[92:95]
.Lst_a5_s2:
	s_or_b64 exec, exec, s[66:67]
	s_and_saveexec_b64 s[66:67], s[12:13]
	s_cbranch_execz .Lst_a5_s3
	ds_write_b128 v253, v[96:99]

.Lst_a5_nold:
.Lst_bar2_5:
	s_waitcnt lgkmcnt(0)
	s_barrier
	s_add_i32 s69, s69, 6
	s_addk_i32 s68, 0x180
	s_cmp_lt_u32 s69, s47
	s_cbranch_scc1 .Lst_top
